# compress cache-stream loads: default cache policy instead of nt (the two 16B halves of each line share one fetch)
# speedup vs baseline: 1.0255x; 1.0105x over previous
; template <bool SAMPLE>
; __device__ __forceinline__ void compress_unit(Frame& F, int l, int unit) {
;     ...
;     f32x4 acc[2][2][4];
; #pragma unroll
;     for (int j = 0; j < 2; ++j)
; #pragma unroll
;         for (int nt = 0; nt < 2; ++nt)
; #pragma unroll
;             for (int et = 0; et < 4; ++et) acc[j][nt][et] = (f32x4){0.f, 0.f, 0.f, 0.f};
;     size_t xoff[2];
; #pragma unroll
;     for (int nt = 0; nt < 2; ++nt) { const int blk = n0 + 4 * nt + nl;
;         if (SAMPLE) { const int page = pt[b * 128 + (blk >> 1)]; xoff[nt] = ((((size_t)l * NPOOL + page) * 128 + (blk & 1) * 64) * 4) * 256 + k * 64 + 8 * q; }
;         else xoff[nt] = (size_t)(b * SEQ + blk * 64) * NPROJ + C_CK + k * 64 + 8 * q; }
;     bf16x8 ra[2][2][4];
;     f32x4 rx[2][2][2][2];
;     ...
;     CMP_LOAD(0, w * 8);
.LBB0_575:
	s_lshl_b32 s24, s14, 3
	s_and_b32 s16, s24, 0xf8
	v_or_b32_e32 v2, s16, v231
	s_ashr_i32 s17, s14, 5
	v_lshrrev_b32_e32 v2, 1, v2
	v_lshl_or_b32 v2, s17, 7, v2
	v_ashrrev_i32_e32 v3, 31, v2
	v_lshl_add_u64 v[2:3], v[2:3], 2, s[46:47]
	global_load_dword v14, v[2:3], off
	global_load_dword v16, v[2:3], off offset:8
	global_load_dwordx4 v[6:9], v[210:211], off
	global_load_dwordx4 v[10:13], v[212:213], off
	s_nop 0
	global_load_dwordx4 v[2:5], v[208:209], off
	global_load_dwordx4 v[22:25], v[208:209], off offset:64
	global_load_dwordx4 v[26:29], v[208:209], off offset:2048
	global_load_dwordx4 v[30:33], v[208:209], off offset:2112
	global_load_dwordx4 v[38:41], v[214:215], off
	global_load_dwordx4 v[42:45], v[216:217], off
	v_mov_b32_e32 v34, 0
	s_mov_b64 s[66:67], 0
	v_mov_b64_e32 v[224:225], v[218:219]
	v_mov_b32_e32 v35, v34
	v_mov_b32_e32 v36, v34
	v_mov_b32_e32 v37, v34
	v_mov_b32_e32 v50, v34
	v_mov_b32_e32 v51, v34
	v_mov_b32_e32 v52, v34
	v_mov_b32_e32 v53, v34
	v_mov_b32_e32 v58, v34
	v_mov_b32_e32 v59, v34
	v_mov_b32_e32 v60, v34
	v_mov_b32_e32 v61, v34
	v_mov_b32_e32 v62, v34
	v_mov_b32_e32 v63, v34
	v_mov_b32_e32 v64, v34
	v_mov_b32_e32 v65, v34
	v_mov_b32_e32 v66, v34
	v_mov_b32_e32 v67, v34
	v_mov_b32_e32 v68, v34
	v_mov_b32_e32 v69, v34
	v_mov_b32_e32 v70, v34
	v_mov_b32_e32 v71, v34
	v_mov_b32_e32 v72, v34
	v_mov_b32_e32 v73, v34
	v_mov_b32_e32 v74, v34
	v_mov_b32_e32 v75, v34
	v_mov_b32_e32 v76, v34
	v_mov_b32_e32 v77, v34
	v_mov_b32_e32 v78, v34
	v_mov_b32_e32 v79, v34
	v_mov_b32_e32 v80, v34
	v_mov_b32_e32 v81, v34
	v_mov_b32_e32 v86, v34
	v_mov_b32_e32 v87, v34
	v_mov_b32_e32 v88, v34
	v_mov_b32_e32 v89, v34
	v_mov_b32_e32 v94, v34
	v_mov_b32_e32 v95, v34
	v_mov_b32_e32 v96, v34
	v_mov_b32_e32 v97, v34
	v_mov_b32_e32 v100, v34
	v_mov_b32_e32 v101, v34
	v_mov_b32_e32 v102, v34
	v_mov_b32_e32 v103, v34
	v_mov_b32_e32 v104, v34
	v_mov_b32_e32 v105, v34
	v_mov_b32_e32 v106, v34
	v_mov_b32_e32 v107, v34
	v_mov_b32_e32 v108, v34
	v_mov_b32_e32 v109, v34
	v_mov_b32_e32 v110, v34
	v_mov_b32_e32 v111, v34
	v_mov_b32_e32 v112, v34
	v_mov_b32_e32 v113, v34
	v_mov_b32_e32 v114, v34
	v_mov_b32_e32 v115, v34
	v_mov_b32_e32 v116, v34
	v_mov_b32_e32 v117, v34
	v_mov_b32_e32 v118, v34
	v_mov_b32_e32 v119, v34
	v_mov_b32_e32 v124, v34
	v_mov_b32_e32 v125, v34
	v_mov_b32_e32 v126, v34
	v_mov_b32_e32 v127, v34
	s_waitcnt vmcnt(9)
	v_ashrrev_i32_e32 v15, 31, v14
	s_waitcnt vmcnt(8)
	v_ashrrev_i32_e32 v17, 31, v16
	v_lshl_add_u64 v[14:15], s[48:49], 0, v[14:15]
	v_lshl_add_u64 v[16:17], s[48:49], 0, v[16:17]
	v_lshlrev_b64 v[14:15], 19, v[14:15]
	v_lshlrev_b64 v[16:17], 19, v[16:17]
	v_or_b32_e32 v14, v14, v244
	v_or_b32_e32 v16, v16, v244
	v_lshl_add_u64 v[220:221], s[44:45], 0, v[14:15]
	v_lshl_add_u64 v[222:223], s[44:45], 0, v[16:17]
	global_load_dwordx4 v[14:17], v[220:221], off offset:16
	global_load_dwordx4 v[18:21], v[220:221], off
	global_load_dwordx4 v[46:49], v[222:223], off offset:16
	global_load_dwordx4 v[82:85], v[222:223], off
	global_load_dwordx4 v[90:93], v[220:221], off offset:144
	global_load_dwordx4 v[54:57], v[220:221], off offset:128
	global_load_dwordx4 v[128:131], v[222:223], off offset:144
	global_load_dwordx4 v[120:123], v[222:223], off offset:128
	s_branch .LBB0_577

; template <bool SAMPLE>
; __device__ __forceinline__ void compress_unit(Frame& F, int l, int unit) {
;     ...
;     CMP_LOAD(0, w * 8);
; #pragma unroll 1
;     for (int li = 0; li < 8; ++li) { const int lpos = w * 8 + li;
;         CMP_LOAD(1, lpos); __builtin_amdgcn_sched_barrier(0);
;         CMP_MMA(0); __builtin_amdgcn_sched_barrier(0);
;         if (li < 7) CMP_LOAD(0, lpos + 1);
;         __builtin_amdgcn_sched_barrier(0);
;         CMP_MMA(1); __builtin_amdgcn_sched_barrier(0);
;     }
.LBB0_577:
	s_mov_b32 s22, 0x7e000
	v_add_co_u32_e32 v136, vcc, s22, v224
	s_mov_b32 s22, 0x7f000
	s_nop 0
	v_addc_co_u32_e32 v137, vcc, 0, v225, vcc
	v_add_co_u32_e32 v144, vcc, s22, v224
	v_lshl_add_u64 v[228:229], v[220:221], 0, s[66:67]
	s_nop 0
	v_addc_co_u32_e32 v145, vcc, 0, v225, vcc
	v_lshl_add_u64 v[226:227], v[222:223], 0, s[66:67]
	global_load_dwordx4 v[188:191], v[228:229], off offset:1040
	global_load_dwordx4 v[192:195], v[228:229], off offset:1024
	global_load_dwordx4 v[176:179], v[226:227], off offset:1040
	global_load_dwordx4 v[184:187], v[226:227], off offset:1024
	global_load_dwordx4 v[156:159], v[136:137], off offset:2048
	global_load_dwordx4 v[132:135], v[136:137], off offset:64
	global_load_dwordx4 v[164:167], v[144:145], off offset:-4096
	s_nop 0
	global_load_dwordx4 v[136:139], v[136:137], off offset:2112
	s_nop 0
	global_load_dwordx4 v[168:171], v[144:145], off
	global_load_dwordx4 v[140:143], v[144:145], off offset:64
	global_load_dwordx4 v[172:175], v[144:145], off offset:2048
	s_nop 0
	global_load_dwordx4 v[144:147], v[144:145], off offset:2112
	s_nop 0
	global_load_dwordx4 v[160:163], v[228:229], off offset:1168
	global_load_dwordx4 v[180:183], v[228:229], off offset:1152
	global_load_dwordx4 v[148:151], v[226:227], off offset:1168
	global_load_dwordx4 v[152:155], v[226:227], off offset:1152
	s_waitcnt vmcnt(22)
	v_cvt_pk_bf16_f32 v246, v18, v19
	v_cvt_pk_bf16_f32 v247, v20, v21
	v_cvt_pk_bf16_f32 v248, v14, v15
	v_cvt_pk_bf16_f32 v249, v16, v17
	s_nop 1
	v_mfma_f32_16x16x32_bf16 v[34:37], v[2:5], v[246:249], v[34:37]
	v_mfma_f32_16x16x32_bf16 v[50:53], v[26:29], v[246:249], v[50:53]
	v_mfma_f32_16x16x32_bf16 v[58:61], v[6:9], v[246:249], v[58:61]
	v_mfma_f32_16x16x32_bf16 v[62:65], v[10:13], v[246:249], v[62:65]
	s_waitcnt vmcnt(20)
	v_cvt_pk_bf16_f32 v246, v82, v83
	v_cvt_pk_bf16_f32 v247, v84, v85
	v_cvt_pk_bf16_f32 v248, v46, v47
	v_cvt_pk_bf16_f32 v249, v48, v49
	s_nop 1
	v_mfma_f32_16x16x32_bf16 v[66:69], v[2:5], v[246:249], v[66:69]
	v_mfma_f32_16x16x32_bf16 v[70:73], v[26:29], v[246:249], v[70:73]
	v_mfma_f32_16x16x32_bf16 v[74:77], v[6:9], v[246:249], v[74:77]
	v_mfma_f32_16x16x32_bf16 v[78:81], v[10:13], v[246:249], v[78:81]
	s_waitcnt vmcnt(18)
	v_cvt_pk_bf16_f32 v246, v54, v55
	v_cvt_pk_bf16_f32 v247, v56, v57
	v_cvt_pk_bf16_f32 v248, v90, v91
	v_cvt_pk_bf16_f32 v249, v92, v93
	s_nop 1
	v_mfma_f32_16x16x32_bf16 v[34:37], v[22:25], v[246:249], v[34:37]
	v_mfma_f32_16x16x32_bf16 v[50:53], v[30:33], v[246:249], v[50:53]
	v_mfma_f32_16x16x32_bf16 v[58:61], v[38:41], v[246:249], v[58:61]
	v_mfma_f32_16x16x32_bf16 v[62:65], v[42:45], v[246:249], v[62:65]
	s_waitcnt vmcnt(16)
	v_cvt_pk_bf16_f32 v246, v120, v121
	v_cvt_pk_bf16_f32 v247, v122, v123
	v_cvt_pk_bf16_f32 v248, v128, v129
	v_cvt_pk_bf16_f32 v249, v130, v131
	s_nop 1
	v_mfma_f32_16x16x32_bf16 v[66:69], v[22:25], v[246:249], v[66:69]
	v_mfma_f32_16x16x32_bf16 v[70:73], v[30:33], v[246:249], v[70:73]
	v_mfma_f32_16x16x32_bf16 v[74:77], v[38:41], v[246:249], v[74:77]
	v_mfma_f32_16x16x32_bf16 v[78:81], v[42:45], v[246:249], v[78:81]
	s_cmpk_eq_i32 s66, 0x7000
	s_cbranch_scc1 .LBB0_576
	v_add_co_u32_e32 v42, vcc, 0x1000, v224
	v_lshl_add_u64 v[2:3], v[228:229], 0, s[96:97]
	s_nop 0
	v_addc_co_u32_e32 v43, vcc, 0, v225, vcc
	v_add_co_u32_e32 v54, vcc, 0x1000, v228
	v_lshl_add_u64 v[46:47], v[226:227], 0, s[96:97]
	s_nop 0
	v_addc_co_u32_e32 v55, vcc, 0, v229, vcc
	global_load_dwordx4 v[18:21], v[54:55], off
	global_load_dwordx4 v[14:17], v[2:3], off offset:16
	s_nop 0
	global_load_dwordx4 v[2:5], v[224:225], off
	global_load_dwordx4 v[22:25], v[224:225], off offset:64
	global_load_dwordx4 v[26:29], v[224:225], off offset:2048
	global_load_dwordx4 v[30:33], v[224:225], off offset:2112
	global_load_dwordx4 v[6:9], v[42:43], off
	global_load_dwordx4 v[38:41], v[42:43], off offset:64
	global_load_dwordx4 v[10:13], v[42:43], off offset:2048
	s_nop 0
	global_load_dwordx4 v[42:45], v[42:43], off offset:2112
	v_add_co_u32_e32 v90, vcc, 0x1000, v226
	v_lshl_add_u64 v[92:93], v[228:229], 0, s[6:7]
	s_nop 0
	v_addc_co_u32_e32 v91, vcc, 0, v227, vcc
	v_lshl_add_u64 v[128:129], v[226:227], 0, s[6:7]
	global_load_dwordx4 v[46:49], v[46:47], off offset:16
	s_nop 0
	global_load_dwordx4 v[54:57], v[54:55], off offset:128
	s_nop 0
	global_load_dwordx4 v[82:85], v[90:91], off
	global_load_dwordx4 v[120:123], v[90:91], off offset:128
	s_nop 0
	global_load_dwordx4 v[90:93], v[92:93], off offset:16
	s_nop 0
	global_load_dwordx4 v[128:131], v[128:129], off offset:16
	s_branch .LBB0_576
